# phase_norm row loops rewritten by hand: next row's x loads and this row's scale/shift loads in flight during the reduction (both norm instances); same arithmetic order
# speedup vs baseline: 1.0170x; 1.0063x over previous
.LBB0_88:
	s_andn2_b64 vcc, exec, s[0:1]
	s_cbranch_vccnz .LBB0_115
	v_readlane_b32 s0, v253, 62
	s_cmp_gt_i32 s0, 5
	s_mov_b64 s[0:1], -1
	s_cbranch_scc0 .LBB0_94
	v_mbcnt_lo_u32_b32 v0, -1, 0
	v_mbcnt_hi_u32_b32 v0, -1, v0
	v_mov_b32_e32 v1, v0
	v_readlane_b32 s0, v252, 6
	s_nop 1
	v_or_b32_e32 v2, s0, v1
	v_ashrrev_i32_e32 v2, 6, v2
	v_readlane_b32 s0, v252, 24
	s_nop 1
	v_add_u32_e32 v34, s0, v2
	s_mov_b32 s0, 0x8000
	v_cmp_gt_i32_e32 vcc, s0, v34
	s_and_saveexec_b64 s[0:1], vcc
	v_readlane_b32 s24, v253, 58
	s_movk_i32 s6, 0x7fff
	v_readlane_b32 s25, v253, 59
	s_cbranch_execz .LBB0_93
	v_and_b32_e32 v2, 64, v0
	v_add_u32_e32 v2, 64, v2
	v_xor_b32_e32 v3, 32, v0
	v_cmp_lt_i32_e32 vcc, v3, v2
	v_readlane_b32 s4, v253, 56
	v_readlane_b32 s5, v253, 57
	v_cndmask_b32_e32 v3, v0, v3, vcc
	s_waitcnt vmcnt(0)
	v_lshlrev_b32_e32 v70, 2, v3
	v_xor_b32_e32 v3, 16, v0
	v_cmp_lt_i32_e32 vcc, v3, v2
	s_load_dwordx16 s[8:23], s[4:5], 0x8
	v_readlane_b32 s2, v253, 54
	v_cndmask_b32_e32 v3, v0, v3, vcc
	v_lshlrev_b32_e32 v71, 2, v3
	v_xor_b32_e32 v3, 8, v0
	v_cmp_lt_i32_e32 vcc, v3, v2
	v_readlane_b32 s3, v253, 55
	s_lshl_b32 s2, s2, 11
	v_cndmask_b32_e32 v3, v0, v3, vcc
	v_lshlrev_b32_e32 v72, 2, v3
	v_xor_b32_e32 v3, 4, v0
	v_cmp_lt_i32_e32 vcc, v3, v2
	s_ashr_i32 s3, s2, 31
	v_and_b32_e32 v1, 63, v1
	v_cndmask_b32_e32 v3, v0, v3, vcc
	v_lshlrev_b32_e32 v73, 2, v3
	v_xor_b32_e32 v3, 2, v0
	v_cmp_lt_i32_e32 vcc, v3, v2
	s_lshl_b64 s[2:3], s[2:3], 2
	s_waitcnt lgkmcnt(0)
	s_add_u32 s2, s18, s2
	v_cndmask_b32_e32 v3, v0, v3, vcc
	v_lshlrev_b32_e32 v74, 2, v3
	v_xor_b32_e32 v3, 1, v0
	v_cmp_lt_i32_e32 vcc, v3, v2
	s_addc_u32 s3, s19, s3
	v_mov_b32_e32 v13, v17
	v_cndmask_b32_e32 v0, v0, v3, vcc
	v_lshlrev_b32_e32 v75, 2, v0
	v_lshlrev_b32_e32 v0, 2, v1
	v_or_b32_e32 v10, 0x400, v0
	v_lshlrev_b32_e32 v12, 2, v10
	v_lshl_add_u64 v[38:39], s[2:3], 0, v[12:13]
	v_or_b32_e32 v12, 0x500, v0
	s_load_dwordx16 s[8:23], s[4:5], 0xc8
	v_lshlrev_b32_e32 v14, 2, v12
	v_mov_b32_e32 v15, v17
	v_lshl_add_u64 v[40:41], s[2:3], 0, v[14:15]
	v_or_b32_e32 v14, 0x600, v0
	v_lshlrev_b32_e32 v18, 2, v14
	v_mov_b32_e32 v19, v17
	v_lshlrev_b32_e32 v2, 4, v1
	v_mov_b32_e32 v3, v17
	v_lshl_add_u64 v[42:43], s[2:3], 0, v[18:19]
	v_or_b32_e32 v18, 0x700, v0
	v_lshl_add_u64 v[36:37], s[2:3], 0, v[2:3]
	v_lshlrev_b32_e32 v20, 2, v18
	v_mov_b32_e32 v21, v17
	s_waitcnt lgkmcnt(0)
	v_lshl_add_u64 v[46:47], s[20:21], 0, v[2:3]
	v_lshlrev_b32_e32 v2, 3, v1
	v_or_b32_e32 v4, 0x100, v0
	v_or_b32_e32 v6, 0x200, v0
	v_or_b32_e32 v8, 0x300, v0
	v_lshl_add_u64 v[44:45], s[2:3], 0, v[20:21]
	v_lshl_add_u64 v[2:3], s[22:23], 0, v[2:3]
	s_mov_b64 s[2:3], 0x7a00000
	v_lshl_add_u64 v[48:49], v[2:3], 0, s[2:3]
	s_mov_b64 s[2:3], 0
	v_lshlrev_b32_e32 v16, 2, v0
	v_lshlrev_b32_e32 v50, 2, v4
	v_lshlrev_b32_e32 v52, 2, v6
	v_lshlrev_b32_e32 v54, 2, v8
	v_lshlrev_b32_e32 v56, 2, v10
	v_lshlrev_b32_e32 v58, 2, v12
	v_lshlrev_b32_e32 v60, 2, v14
	v_lshlrev_b32_e32 v62, 2, v18
	v_readfirstlane_b32 s2, v34
	v_readfirstlane_b32 s4, v46
	v_readfirstlane_b32 s5, v47
	v_readfirstlane_b32 s8, v36
	v_readfirstlane_b32 s9, v37
	v_readfirstlane_b32 s10, v48
	v_readfirstlane_b32 s11, v49
	v_and_b32_e32 v18, 63, v221
	v_lshlrev_b32_e32 v18, 4, v18
	v_add_u32_e32 v19, 0x1000, v18
	s_nop 2
	global_load_dwordx4 v[76:79], v18, s[8:9] offset:0
	global_load_dwordx4 v[80:83], v18, s[8:9] offset:1024
	global_load_dwordx4 v[84:87], v18, s[8:9] offset:2048
	global_load_dwordx4 v[88:91], v18, s[8:9] offset:3072
	global_load_dwordx4 v[92:95], v19, s[8:9] offset:0
	global_load_dwordx4 v[96:99], v19, s[8:9] offset:1024
	global_load_dwordx4 v[100:103], v19, s[8:9] offset:2048
	global_load_dwordx4 v[104:107], v19, s[8:9] offset:3072
	s_lshl_b32 s16, s2, 13
	v_add_u32_e32 v20, s16, v18
	v_add_u32_e32 v21, s16, v19
	global_load_dwordx4 v[108:111], v20, s[4:5] offset:0
	global_load_dwordx4 v[112:115], v20, s[4:5] offset:1024
	global_load_dwordx4 v[116:119], v20, s[4:5] offset:2048
	global_load_dwordx4 v[120:123], v20, s[4:5] offset:3072
	global_load_dwordx4 v[124:127], v21, s[4:5] offset:0
	global_load_dwordx4 v[128:131], v21, s[4:5] offset:1024
	global_load_dwordx4 v[132:135], v21, s[4:5] offset:2048
	global_load_dwordx4 v[136:139], v21, s[4:5] offset:3072
.Lnorm_n2_loop:
	s_lshr_b32 s16, s2, 11
	s_mul_i32 s16, s16, 0xc000
	s_add_u32 s12, s24, s16
	s_addc_u32 s13, s25, 0
	s_add_u32 s14, s12, 0x6000
	s_addc_u32 s15, s13, 0
	s_add_u32 s12, s12, 0x8000
	s_addc_u32 s13, s13, 0
	global_load_dwordx4 v[148:151], v18, s[12:13] offset:0
	global_load_dwordx4 v[232:235], v18, s[14:15] offset:0
	global_load_dwordx4 v[152:155], v18, s[12:13] offset:1024
	global_load_dwordx4 v[236:239], v18, s[14:15] offset:1024
	global_load_dwordx4 v[156:159], v18, s[12:13] offset:2048
	global_load_dwordx4 v[240:243], v18, s[14:15] offset:2048
	global_load_dwordx4 v[160:163], v18, s[12:13] offset:3072
	global_load_dwordx4 v[244:247], v18, s[14:15] offset:3072
	global_load_dwordx4 v[164:167], v19, s[12:13] offset:0
	global_load_dwordx4 v[248:251], v19, s[14:15] offset:0
	global_load_dwordx4 v[168:171], v19, s[12:13] offset:1024
	global_load_dwordx4 v[8:11], v19, s[14:15] offset:1024
	global_load_dwordx4 v[0:3], v19, s[12:13] offset:2048
	global_load_dwordx4 v[12:15], v19, s[14:15] offset:2048
	global_load_dwordx4 v[4:7], v19, s[12:13] offset:3072
	global_load_dwordx4 v[208:211], v19, s[14:15] offset:3072
	s_add_i32 s3, s2, s60
	s_cmp_gt_i32 s3, s6
	s_cselect_b32 s17, s2, s3
	s_lshl_b32 s16, s17, 13
	v_add_u32_e32 v20, s16, v18
	v_add_u32_e32 v21, s16, v19
	global_load_dwordx4 v[176:179], v20, s[4:5] offset:0
	global_load_dwordx4 v[180:183], v20, s[4:5] offset:1024
	global_load_dwordx4 v[184:187], v20, s[4:5] offset:2048
	global_load_dwordx4 v[188:191], v20, s[4:5] offset:3072
	global_load_dwordx4 v[192:195], v21, s[4:5] offset:0
	global_load_dwordx4 v[196:199], v21, s[4:5] offset:1024
	global_load_dwordx4 v[200:203], v21, s[4:5] offset:2048
	global_load_dwordx4 v[204:207], v21, s[4:5] offset:3072
	s_waitcnt vmcnt(24)
	v_mul_f32_e32 v23, v109, v109
	v_fmac_f32_e32 v23, v108, v108
	v_fmac_f32_e32 v23, v110, v110
	v_fmac_f32_e32 v23, v111, v111
	v_mul_f32_e32 v24, v113, v113
	v_fmac_f32_e32 v24, v112, v112
	v_fmac_f32_e32 v24, v114, v114
	v_fmac_f32_e32 v24, v115, v115
	v_add_f32_e32 v23, v23, v24
	v_mul_f32_e32 v24, v117, v117
	v_fmac_f32_e32 v24, v116, v116
	v_fmac_f32_e32 v24, v118, v118
	v_fmac_f32_e32 v24, v119, v119
	v_add_f32_e32 v23, v23, v24
	v_mul_f32_e32 v24, v121, v121
	v_fmac_f32_e32 v24, v120, v120
	v_fmac_f32_e32 v24, v122, v122
	v_fmac_f32_e32 v24, v123, v123
	v_add_f32_e32 v23, v23, v24
	v_mul_f32_e32 v24, v125, v125
	v_fmac_f32_e32 v24, v124, v124
	v_fmac_f32_e32 v24, v126, v126
	v_fmac_f32_e32 v24, v127, v127
	v_add_f32_e32 v23, v23, v24
	v_mul_f32_e32 v24, v129, v129
	v_fmac_f32_e32 v24, v128, v128
	v_fmac_f32_e32 v24, v130, v130
	v_fmac_f32_e32 v24, v131, v131
	v_add_f32_e32 v23, v23, v24
	v_mul_f32_e32 v24, v133, v133
	v_fmac_f32_e32 v24, v132, v132
	v_fmac_f32_e32 v24, v134, v134
	v_fmac_f32_e32 v24, v135, v135
	v_add_f32_e32 v23, v23, v24
	v_mul_f32_e32 v24, v137, v137
	v_fmac_f32_e32 v24, v136, v136
	v_fmac_f32_e32 v24, v138, v138
	v_fmac_f32_e32 v24, v139, v139
	v_add_f32_e32 v23, v23, v24
	s_nop 0
	ds_bpermute_b32 v24, v70, v23
	s_waitcnt lgkmcnt(0)
	v_add_f32_e32 v23, v23, v24
	s_nop 0
	ds_bpermute_b32 v24, v71, v23
	s_waitcnt lgkmcnt(0)
	v_add_f32_e32 v23, v23, v24
	s_nop 0
	ds_bpermute_b32 v24, v72, v23
	s_waitcnt lgkmcnt(0)
	v_add_f32_e32 v23, v23, v24
	s_nop 0
	ds_bpermute_b32 v24, v73, v23
	s_waitcnt lgkmcnt(0)
	v_add_f32_e32 v23, v23, v24
	s_nop 0
	ds_bpermute_b32 v24, v74, v23
	s_waitcnt lgkmcnt(0)
	v_add_f32_e32 v23, v23, v24
	s_nop 0
	ds_bpermute_b32 v24, v75, v23
	s_waitcnt lgkmcnt(0)
	v_add_f32_e32 v23, v23, v24
	v_fmamk_f32 v23, v23, 0x3a000000, v216
	v_mul_f32_e32 v24, 0x4b800000, v23
	v_cmp_gt_f32_e32 vcc, s45, v23
	s_nop 1
	v_cndmask_b32_e32 v23, v23, v24, vcc
	v_rsq_f32_e32 v23, v23
	s_nop 0
	v_mul_f32_e32 v24, 0x45800000, v23
	v_cndmask_b32_e32 v25, v23, v24, vcc
	s_lshl_b32 s16, s2, 12
	v_lshrrev_b32_e32 v22, 1, v18
	v_add_u32_e32 v22, s16, v22
	s_waitcnt vmcnt(8)
	v_mul_f32_e32 v108, v108, v25
	v_mul_f32_e32 v109, v109, v25
	v_mul_f32_e32 v110, v110, v25
	v_mul_f32_e32 v111, v111, v25
	v_mul_f32_e32 v108, v76, v108
	v_mul_f32_e32 v109, v77, v109
	v_mul_f32_e32 v110, v78, v110
	v_mul_f32_e32 v111, v79, v111
	v_add_f32_e32 v148, 1.0, v148
	v_add_f32_e32 v149, 1.0, v149
	v_add_f32_e32 v150, 1.0, v150
	v_add_f32_e32 v151, 1.0, v151
	v_fma_f32 v108, v148, v108, v232
	v_fma_f32 v109, v149, v109, v233
	v_fma_f32 v110, v150, v110, v234
	v_fma_f32 v111, v151, v111, v235
	v_cvt_pk_bf16_f32 v108, v108, v109
	v_cvt_pk_bf16_f32 v109, v110, v111
	global_store_dwordx2 v22, v[108:109], s[10:11] offset:0
	v_mul_f32_e32 v112, v112, v25
	v_mul_f32_e32 v113, v113, v25
	v_mul_f32_e32 v114, v114, v25
	v_mul_f32_e32 v115, v115, v25
	v_mul_f32_e32 v112, v80, v112
	v_mul_f32_e32 v113, v81, v113
	v_mul_f32_e32 v114, v82, v114
	v_mul_f32_e32 v115, v83, v115
	v_add_f32_e32 v152, 1.0, v152
	v_add_f32_e32 v153, 1.0, v153
	v_add_f32_e32 v154, 1.0, v154
	v_add_f32_e32 v155, 1.0, v155
	v_fma_f32 v112, v152, v112, v236
	v_fma_f32 v113, v153, v113, v237
	v_fma_f32 v114, v154, v114, v238
	v_fma_f32 v115, v155, v115, v239
	v_cvt_pk_bf16_f32 v112, v112, v113
	v_cvt_pk_bf16_f32 v113, v114, v115
	global_store_dwordx2 v22, v[112:113], s[10:11] offset:512
	v_mul_f32_e32 v116, v116, v25
	v_mul_f32_e32 v117, v117, v25
	v_mul_f32_e32 v118, v118, v25
	v_mul_f32_e32 v119, v119, v25
	v_mul_f32_e32 v116, v84, v116
	v_mul_f32_e32 v117, v85, v117
	v_mul_f32_e32 v118, v86, v118
	v_mul_f32_e32 v119, v87, v119
	v_add_f32_e32 v156, 1.0, v156
	v_add_f32_e32 v157, 1.0, v157
	v_add_f32_e32 v158, 1.0, v158
	v_add_f32_e32 v159, 1.0, v159
	v_fma_f32 v116, v156, v116, v240
	v_fma_f32 v117, v157, v117, v241
	v_fma_f32 v118, v158, v118, v242
	v_fma_f32 v119, v159, v119, v243
	v_cvt_pk_bf16_f32 v116, v116, v117
	v_cvt_pk_bf16_f32 v117, v118, v119
	global_store_dwordx2 v22, v[116:117], s[10:11] offset:1024
	v_mul_f32_e32 v120, v120, v25
	v_mul_f32_e32 v121, v121, v25
	v_mul_f32_e32 v122, v122, v25
	v_mul_f32_e32 v123, v123, v25
	v_mul_f32_e32 v120, v88, v120
	v_mul_f32_e32 v121, v89, v121
	v_mul_f32_e32 v122, v90, v122
	v_mul_f32_e32 v123, v91, v123
	v_add_f32_e32 v160, 1.0, v160
	v_add_f32_e32 v161, 1.0, v161
	v_add_f32_e32 v162, 1.0, v162
	v_add_f32_e32 v163, 1.0, v163
	v_fma_f32 v120, v160, v120, v244
	v_fma_f32 v121, v161, v121, v245
	v_fma_f32 v122, v162, v122, v246
	v_fma_f32 v123, v163, v123, v247
	v_cvt_pk_bf16_f32 v120, v120, v121
	v_cvt_pk_bf16_f32 v121, v122, v123
	global_store_dwordx2 v22, v[120:121], s[10:11] offset:1536
	v_mul_f32_e32 v124, v124, v25
	v_mul_f32_e32 v125, v125, v25
	v_mul_f32_e32 v126, v126, v25
	v_mul_f32_e32 v127, v127, v25
	v_mul_f32_e32 v124, v92, v124
	v_mul_f32_e32 v125, v93, v125
	v_mul_f32_e32 v126, v94, v126
	v_mul_f32_e32 v127, v95, v127
	v_add_f32_e32 v164, 1.0, v164
	v_add_f32_e32 v165, 1.0, v165
	v_add_f32_e32 v166, 1.0, v166
	v_add_f32_e32 v167, 1.0, v167
	v_fma_f32 v124, v164, v124, v248
	v_fma_f32 v125, v165, v125, v249
	v_fma_f32 v126, v166, v126, v250
	v_fma_f32 v127, v167, v127, v251
	v_cvt_pk_bf16_f32 v124, v124, v125
	v_cvt_pk_bf16_f32 v125, v126, v127
	global_store_dwordx2 v22, v[124:125], s[10:11] offset:2048
	v_mul_f32_e32 v128, v128, v25
	v_mul_f32_e32 v129, v129, v25
	v_mul_f32_e32 v130, v130, v25
	v_mul_f32_e32 v131, v131, v25
	v_mul_f32_e32 v128, v96, v128
	v_mul_f32_e32 v129, v97, v129
	v_mul_f32_e32 v130, v98, v130
	v_mul_f32_e32 v131, v99, v131
	v_add_f32_e32 v168, 1.0, v168
	v_add_f32_e32 v169, 1.0, v169
	v_add_f32_e32 v170, 1.0, v170
	v_add_f32_e32 v171, 1.0, v171
	v_fma_f32 v128, v168, v128, v8
	v_fma_f32 v129, v169, v129, v9
	v_fma_f32 v130, v170, v130, v10
	v_fma_f32 v131, v171, v131, v11
	v_cvt_pk_bf16_f32 v128, v128, v129
	v_cvt_pk_bf16_f32 v129, v130, v131
	global_store_dwordx2 v22, v[128:129], s[10:11] offset:2560
	v_mul_f32_e32 v132, v132, v25
	v_mul_f32_e32 v133, v133, v25
	v_mul_f32_e32 v134, v134, v25
	v_mul_f32_e32 v135, v135, v25
	v_mul_f32_e32 v132, v100, v132
	v_mul_f32_e32 v133, v101, v133
	v_mul_f32_e32 v134, v102, v134
	v_mul_f32_e32 v135, v103, v135
	v_add_f32_e32 v0, 1.0, v0
	v_add_f32_e32 v1, 1.0, v1
	v_add_f32_e32 v2, 1.0, v2
	v_add_f32_e32 v3, 1.0, v3
	v_fma_f32 v132, v0, v132, v12
	v_fma_f32 v133, v1, v133, v13
	v_fma_f32 v134, v2, v134, v14
	v_fma_f32 v135, v3, v135, v15
	v_cvt_pk_bf16_f32 v132, v132, v133
	v_cvt_pk_bf16_f32 v133, v134, v135
	global_store_dwordx2 v22, v[132:133], s[10:11] offset:3072
	v_mul_f32_e32 v136, v136, v25
	v_mul_f32_e32 v137, v137, v25
	v_mul_f32_e32 v138, v138, v25
	v_mul_f32_e32 v139, v139, v25
	v_mul_f32_e32 v136, v104, v136
	v_mul_f32_e32 v137, v105, v137
	v_mul_f32_e32 v138, v106, v138
	v_mul_f32_e32 v139, v107, v139
	v_add_f32_e32 v4, 1.0, v4
	v_add_f32_e32 v5, 1.0, v5
	v_add_f32_e32 v6, 1.0, v6
	v_add_f32_e32 v7, 1.0, v7
	v_fma_f32 v136, v4, v136, v208
	v_fma_f32 v137, v5, v137, v209
	v_fma_f32 v138, v6, v138, v210
	v_fma_f32 v139, v7, v139, v211
	v_cvt_pk_bf16_f32 v136, v136, v137
	v_cvt_pk_bf16_f32 v137, v138, v139
	global_store_dwordx2 v22, v[136:137], s[10:11] offset:3584
	s_cmp_gt_i32 s3, s6
	s_mov_b32 s2, s3
	s_cbranch_scc1 .Lnorm_n2_done
	s_lshr_b32 s16, s2, 11
	s_mul_i32 s16, s16, 0xc000
	s_add_u32 s12, s24, s16
	s_addc_u32 s13, s25, 0
	s_add_u32 s14, s12, 0x6000
	s_addc_u32 s15, s13, 0
	s_add_u32 s12, s12, 0x8000
	s_addc_u32 s13, s13, 0
	global_load_dwordx4 v[148:151], v18, s[12:13] offset:0
	global_load_dwordx4 v[232:235], v18, s[14:15] offset:0
	global_load_dwordx4 v[152:155], v18, s[12:13] offset:1024
	global_load_dwordx4 v[236:239], v18, s[14:15] offset:1024
	global_load_dwordx4 v[156:159], v18, s[12:13] offset:2048
	global_load_dwordx4 v[240:243], v18, s[14:15] offset:2048
	global_load_dwordx4 v[160:163], v18, s[12:13] offset:3072
	global_load_dwordx4 v[244:247], v18, s[14:15] offset:3072
	global_load_dwordx4 v[164:167], v19, s[12:13] offset:0
	global_load_dwordx4 v[248:251], v19, s[14:15] offset:0
	global_load_dwordx4 v[168:171], v19, s[12:13] offset:1024
	global_load_dwordx4 v[8:11], v19, s[14:15] offset:1024
	global_load_dwordx4 v[0:3], v19, s[12:13] offset:2048
	global_load_dwordx4 v[12:15], v19, s[14:15] offset:2048
	global_load_dwordx4 v[4:7], v19, s[12:13] offset:3072
	global_load_dwordx4 v[208:211], v19, s[14:15] offset:3072
	s_add_i32 s3, s2, s60
	s_cmp_gt_i32 s3, s6
	s_cselect_b32 s17, s2, s3
	s_lshl_b32 s16, s17, 13
	v_add_u32_e32 v20, s16, v18
	v_add_u32_e32 v21, s16, v19
	global_load_dwordx4 v[108:111], v20, s[4:5] offset:0
	global_load_dwordx4 v[112:115], v20, s[4:5] offset:1024
	global_load_dwordx4 v[116:119], v20, s[4:5] offset:2048
	global_load_dwordx4 v[120:123], v20, s[4:5] offset:3072
	global_load_dwordx4 v[124:127], v21, s[4:5] offset:0
	global_load_dwordx4 v[128:131], v21, s[4:5] offset:1024
	global_load_dwordx4 v[132:135], v21, s[4:5] offset:2048
	global_load_dwordx4 v[136:139], v21, s[4:5] offset:3072
	s_waitcnt vmcnt(24)
	v_mul_f32_e32 v23, v177, v177
	v_fmac_f32_e32 v23, v176, v176
	v_fmac_f32_e32 v23, v178, v178
	v_fmac_f32_e32 v23, v179, v179
	v_mul_f32_e32 v24, v181, v181
	v_fmac_f32_e32 v24, v180, v180
	v_fmac_f32_e32 v24, v182, v182
	v_fmac_f32_e32 v24, v183, v183
	v_add_f32_e32 v23, v23, v24
	v_mul_f32_e32 v24, v185, v185
	v_fmac_f32_e32 v24, v184, v184
	v_fmac_f32_e32 v24, v186, v186
	v_fmac_f32_e32 v24, v187, v187
	v_add_f32_e32 v23, v23, v24
	v_mul_f32_e32 v24, v189, v189
	v_fmac_f32_e32 v24, v188, v188
	v_fmac_f32_e32 v24, v190, v190
	v_fmac_f32_e32 v24, v191, v191
	v_add_f32_e32 v23, v23, v24
	v_mul_f32_e32 v24, v193, v193
	v_fmac_f32_e32 v24, v192, v192
	v_fmac_f32_e32 v24, v194, v194
	v_fmac_f32_e32 v24, v195, v195
	v_add_f32_e32 v23, v23, v24
	v_mul_f32_e32 v24, v197, v197
	v_fmac_f32_e32 v24, v196, v196
	v_fmac_f32_e32 v24, v198, v198
	v_fmac_f32_e32 v24, v199, v199
	v_add_f32_e32 v23, v23, v24
	v_mul_f32_e32 v24, v201, v201
	v_fmac_f32_e32 v24, v200, v200
	v_fmac_f32_e32 v24, v202, v202
	v_fmac_f32_e32 v24, v203, v203
	v_add_f32_e32 v23, v23, v24
	v_mul_f32_e32 v24, v205, v205
	v_fmac_f32_e32 v24, v204, v204
	v_fmac_f32_e32 v24, v206, v206
	v_fmac_f32_e32 v24, v207, v207
	v_add_f32_e32 v23, v23, v24
	s_nop 0
	ds_bpermute_b32 v24, v70, v23
	s_waitcnt lgkmcnt(0)
	v_add_f32_e32 v23, v23, v24
	s_nop 0
	ds_bpermute_b32 v24, v71, v23
	s_waitcnt lgkmcnt(0)
	v_add_f32_e32 v23, v23, v24
	s_nop 0
	ds_bpermute_b32 v24, v72, v23
	s_waitcnt lgkmcnt(0)
	v_add_f32_e32 v23, v23, v24
	s_nop 0
	ds_bpermute_b32 v24, v73, v23
	s_waitcnt lgkmcnt(0)
	v_add_f32_e32 v23, v23, v24
	s_nop 0
	ds_bpermute_b32 v24, v74, v23
	s_waitcnt lgkmcnt(0)
	v_add_f32_e32 v23, v23, v24
	s_nop 0
	ds_bpermute_b32 v24, v75, v23
	s_waitcnt lgkmcnt(0)
	v_add_f32_e32 v23, v23, v24
	v_fmamk_f32 v23, v23, 0x3a000000, v216
	v_mul_f32_e32 v24, 0x4b800000, v23
	v_cmp_gt_f32_e32 vcc, s45, v23
	s_nop 1
	v_cndmask_b32_e32 v23, v23, v24, vcc
	v_rsq_f32_e32 v23, v23
	s_nop 0
	v_mul_f32_e32 v24, 0x45800000, v23
	v_cndmask_b32_e32 v25, v23, v24, vcc
	s_lshl_b32 s16, s2, 12
	v_lshrrev_b32_e32 v22, 1, v18
	v_add_u32_e32 v22, s16, v22
	s_waitcnt vmcnt(8)
	v_mul_f32_e32 v176, v176, v25
	v_mul_f32_e32 v177, v177, v25
	v_mul_f32_e32 v178, v178, v25
	v_mul_f32_e32 v179, v179, v25
	v_mul_f32_e32 v176, v76, v176
	v_mul_f32_e32 v177, v77, v177
	v_mul_f32_e32 v178, v78, v178
	v_mul_f32_e32 v179, v79, v179
	v_add_f32_e32 v148, 1.0, v148
	v_add_f32_e32 v149, 1.0, v149
	v_add_f32_e32 v150, 1.0, v150
	v_add_f32_e32 v151, 1.0, v151
	v_fma_f32 v176, v148, v176, v232
	v_fma_f32 v177, v149, v177, v233
	v_fma_f32 v178, v150, v178, v234
	v_fma_f32 v179, v151, v179, v235
	v_cvt_pk_bf16_f32 v176, v176, v177
	v_cvt_pk_bf16_f32 v177, v178, v179
	global_store_dwordx2 v22, v[176:177], s[10:11] offset:0
	v_mul_f32_e32 v180, v180, v25
	v_mul_f32_e32 v181, v181, v25
	v_mul_f32_e32 v182, v182, v25
	v_mul_f32_e32 v183, v183, v25
	v_mul_f32_e32 v180, v80, v180
	v_mul_f32_e32 v181, v81, v181
	v_mul_f32_e32 v182, v82, v182
	v_mul_f32_e32 v183, v83, v183
	v_add_f32_e32 v152, 1.0, v152
	v_add_f32_e32 v153, 1.0, v153
	v_add_f32_e32 v154, 1.0, v154
	v_add_f32_e32 v155, 1.0, v155
	v_fma_f32 v180, v152, v180, v236
	v_fma_f32 v181, v153, v181, v237
	v_fma_f32 v182, v154, v182, v238
	v_fma_f32 v183, v155, v183, v239
	v_cvt_pk_bf16_f32 v180, v180, v181
	v_cvt_pk_bf16_f32 v181, v182, v183
	global_store_dwordx2 v22, v[180:181], s[10:11] offset:512
	v_mul_f32_e32 v184, v184, v25
	v_mul_f32_e32 v185, v185, v25
	v_mul_f32_e32 v186, v186, v25
	v_mul_f32_e32 v187, v187, v25
	v_mul_f32_e32 v184, v84, v184
	v_mul_f32_e32 v185, v85, v185
	v_mul_f32_e32 v186, v86, v186
	v_mul_f32_e32 v187, v87, v187
	v_add_f32_e32 v156, 1.0, v156
	v_add_f32_e32 v157, 1.0, v157
	v_add_f32_e32 v158, 1.0, v158
	v_add_f32_e32 v159, 1.0, v159
	v_fma_f32 v184, v156, v184, v240
	v_fma_f32 v185, v157, v185, v241
	v_fma_f32 v186, v158, v186, v242
	v_fma_f32 v187, v159, v187, v243
	v_cvt_pk_bf16_f32 v184, v184, v185
	v_cvt_pk_bf16_f32 v185, v186, v187
	global_store_dwordx2 v22, v[184:185], s[10:11] offset:1024
	v_mul_f32_e32 v188, v188, v25
	v_mul_f32_e32 v189, v189, v25
	v_mul_f32_e32 v190, v190, v25
	v_mul_f32_e32 v191, v191, v25
	v_mul_f32_e32 v188, v88, v188
	v_mul_f32_e32 v189, v89, v189
	v_mul_f32_e32 v190, v90, v190
	v_mul_f32_e32 v191, v91, v191
	v_add_f32_e32 v160, 1.0, v160
	v_add_f32_e32 v161, 1.0, v161
	v_add_f32_e32 v162, 1.0, v162
	v_add_f32_e32 v163, 1.0, v163
	v_fma_f32 v188, v160, v188, v244
	v_fma_f32 v189, v161, v189, v245
	v_fma_f32 v190, v162, v190, v246
	v_fma_f32 v191, v163, v191, v247
	v_cvt_pk_bf16_f32 v188, v188, v189
	v_cvt_pk_bf16_f32 v189, v190, v191
	global_store_dwordx2 v22, v[188:189], s[10:11] offset:1536
	v_mul_f32_e32 v192, v192, v25
	v_mul_f32_e32 v193, v193, v25
	v_mul_f32_e32 v194, v194, v25
	v_mul_f32_e32 v195, v195, v25
	v_mul_f32_e32 v192, v92, v192
	v_mul_f32_e32 v193, v93, v193
	v_mul_f32_e32 v194, v94, v194
	v_mul_f32_e32 v195, v95, v195
	v_add_f32_e32 v164, 1.0, v164
	v_add_f32_e32 v165, 1.0, v165
	v_add_f32_e32 v166, 1.0, v166
	v_add_f32_e32 v167, 1.0, v167
	v_fma_f32 v192, v164, v192, v248
	v_fma_f32 v193, v165, v193, v249
	v_fma_f32 v194, v166, v194, v250
	v_fma_f32 v195, v167, v195, v251
	v_cvt_pk_bf16_f32 v192, v192, v193
	v_cvt_pk_bf16_f32 v193, v194, v195
	global_store_dwordx2 v22, v[192:193], s[10:11] offset:2048
	v_mul_f32_e32 v196, v196, v25
	v_mul_f32_e32 v197, v197, v25
	v_mul_f32_e32 v198, v198, v25
	v_mul_f32_e32 v199, v199, v25
	v_mul_f32_e32 v196, v96, v196
	v_mul_f32_e32 v197, v97, v197
	v_mul_f32_e32 v198, v98, v198
	v_mul_f32_e32 v199, v99, v199
	v_add_f32_e32 v168, 1.0, v168
	v_add_f32_e32 v169, 1.0, v169
	v_add_f32_e32 v170, 1.0, v170
	v_add_f32_e32 v171, 1.0, v171
	v_fma_f32 v196, v168, v196, v8
	v_fma_f32 v197, v169, v197, v9
	v_fma_f32 v198, v170, v198, v10
	v_fma_f32 v199, v171, v199, v11
	v_cvt_pk_bf16_f32 v196, v196, v197
	v_cvt_pk_bf16_f32 v197, v198, v199
	global_store_dwordx2 v22, v[196:197], s[10:11] offset:2560
	v_mul_f32_e32 v200, v200, v25
	v_mul_f32_e32 v201, v201, v25
	v_mul_f32_e32 v202, v202, v25
	v_mul_f32_e32 v203, v203, v25
	v_mul_f32_e32 v200, v100, v200
	v_mul_f32_e32 v201, v101, v201
	v_mul_f32_e32 v202, v102, v202
	v_mul_f32_e32 v203, v103, v203
	v_add_f32_e32 v0, 1.0, v0
	v_add_f32_e32 v1, 1.0, v1
	v_add_f32_e32 v2, 1.0, v2
	v_add_f32_e32 v3, 1.0, v3
	v_fma_f32 v200, v0, v200, v12
	v_fma_f32 v201, v1, v201, v13
	v_fma_f32 v202, v2, v202, v14
	v_fma_f32 v203, v3, v203, v15
	v_cvt_pk_bf16_f32 v200, v200, v201
	v_cvt_pk_bf16_f32 v201, v202, v203
	global_store_dwordx2 v22, v[200:201], s[10:11] offset:3072
	v_mul_f32_e32 v204, v204, v25
	v_mul_f32_e32 v205, v205, v25
	v_mul_f32_e32 v206, v206, v25
	v_mul_f32_e32 v207, v207, v25
	v_mul_f32_e32 v204, v104, v204
	v_mul_f32_e32 v205, v105, v205
	v_mul_f32_e32 v206, v106, v206
	v_mul_f32_e32 v207, v107, v207
	v_add_f32_e32 v4, 1.0, v4
	v_add_f32_e32 v5, 1.0, v5
	v_add_f32_e32 v6, 1.0, v6
	v_add_f32_e32 v7, 1.0, v7
	v_fma_f32 v204, v4, v204, v208
	v_fma_f32 v205, v5, v205, v209
	v_fma_f32 v206, v6, v206, v210
	v_fma_f32 v207, v7, v207, v211
	v_cvt_pk_bf16_f32 v204, v204, v205
	v_cvt_pk_bf16_f32 v205, v206, v207
	global_store_dwordx2 v22, v[204:205], s[10:11] offset:3584
	s_cmp_gt_i32 s3, s6
	s_mov_b32 s2, s3
	s_cbranch_scc1 .Lnorm_n2_done
	s_branch .Lnorm_n2_loop
.Lnorm_n2_done:
	s_waitcnt vmcnt(0)
.LBB0_93:
	s_or_b64 exec, exec, s[0:1]
	s_mov_b64 s[0:1], 0

.LBB0_1719:
	s_or_b64 exec, exec, s[0:1]
	v_mov_b32_e32 v0, v221
	v_readlane_b32 s0, v252, 6
	s_nop 1
	v_or_b32_e32 v1, s0, v0
	v_ashrrev_i32_e32 v1, 6, v1
	v_readlane_b32 s0, v252, 24
	s_nop 1
	v_add_u32_e32 v30, s0, v1
	s_mov_b32 s0, 0x8000
	v_cmp_gt_i32_e32 vcc, s0, v30
	s_and_saveexec_b64 s[0:1], vcc
	v_readlane_b32 s24, v253, 58
	s_movk_i32 s6, 0x7fff
	v_readlane_b32 s25, v253, 59
	s_cbranch_execz .LBB0_1722
	v_and_b32_e32 v1, 63, v0
	v_and_b32_e32 v0, 64, v221
	v_add_u32_e32 v0, 64, v0
	v_xor_b32_e32 v2, 32, v221
	v_cmp_lt_i32_e32 vcc, v2, v0
	v_readlane_b32 s2, v253, 54
	v_readlane_b32 s8, v253, 22
	v_cndmask_b32_e32 v2, v221, v2, vcc
	v_lshlrev_b32_e32 v66, 2, v2
	v_xor_b32_e32 v2, 16, v221
	v_cmp_lt_i32_e32 vcc, v2, v0
	v_readlane_b32 s3, v253, 55
	s_lshl_b32 s2, s2, 11
	v_cndmask_b32_e32 v2, v221, v2, vcc
	v_lshlrev_b32_e32 v67, 2, v2
	v_xor_b32_e32 v2, 8, v221
	v_cmp_lt_i32_e32 vcc, v2, v0
	v_readlane_b32 s9, v253, 23
	v_readlane_b32 s10, v253, 24
	v_cndmask_b32_e32 v2, v221, v2, vcc
	v_lshlrev_b32_e32 v68, 2, v2
	v_xor_b32_e32 v2, 4, v221
	v_cmp_lt_i32_e32 vcc, v2, v0
	v_readlane_b32 s11, v253, 25
	v_readlane_b32 s12, v253, 26
	v_cndmask_b32_e32 v2, v221, v2, vcc
	v_lshlrev_b32_e32 v69, 2, v2
	v_xor_b32_e32 v2, 2, v221
	v_cmp_lt_i32_e32 vcc, v2, v0
	v_readlane_b32 s13, v253, 27
	s_ashr_i32 s3, s2, 31
	v_cndmask_b32_e32 v2, v221, v2, vcc
	s_waitcnt vmcnt(0)
	v_lshlrev_b32_e32 v70, 2, v2
	v_xor_b32_e32 v2, 1, v221
	v_cmp_lt_i32_e32 vcc, v2, v0
	v_readlane_b32 s14, v253, 28
	v_readlane_b32 s15, v253, 29
	v_readlane_b32 s16, v253, 30
	v_readlane_b32 s17, v253, 31
	s_mov_b64 s[8:9], s[12:13]
	v_cndmask_b32_e32 v0, v221, v2, vcc
	s_lshl_b64 s[2:3], s[2:3], 2
	s_mov_b64 s[10:11], s[14:15]
	s_mov_b64 s[12:13], s[16:17]
	v_lshlrev_b32_e32 v71, 2, v0
	v_lshlrev_b32_e32 v0, 2, v1
	s_add_u32 s2, s12, s2
	v_or_b32_e32 v10, 0x400, v0
	s_addc_u32 s3, s13, s3
	v_lshlrev_b32_e32 v12, 2, v10
	v_mov_b32_e32 v13, v17
	v_lshl_add_u64 v[34:35], s[2:3], 0, v[12:13]
	v_or_b32_e32 v12, 0x500, v0
	v_lshlrev_b32_e32 v14, 2, v12
	v_mov_b32_e32 v15, v17
	v_lshl_add_u64 v[36:37], s[2:3], 0, v[14:15]
	v_or_b32_e32 v14, 0x600, v0
	v_lshlrev_b32_e32 v18, 2, v14
	v_mov_b32_e32 v19, v17
	v_lshl_add_u64 v[38:39], s[2:3], 0, v[18:19]
	v_or_b32_e32 v18, 0x700, v0
	v_lshlrev_b32_e32 v2, 4, v1
	v_mov_b32_e32 v3, v17
	v_lshlrev_b32_e32 v20, 2, v18
	v_mov_b32_e32 v21, v17
	v_readlane_b32 s18, v253, 32
	v_readlane_b32 s19, v253, 33
	v_readlane_b32 s20, v253, 34
	v_readlane_b32 s21, v253, 35
	v_readlane_b32 s22, v253, 36
	v_readlane_b32 s23, v253, 37
	v_lshl_add_u64 v[32:33], s[2:3], 0, v[2:3]
	v_lshl_add_u64 v[40:41], s[2:3], 0, v[20:21]
	v_readlane_b32 s2, v253, 60
	v_readlane_b32 s3, v253, 61
	v_readlane_b32 s8, v253, 38
	v_readlane_b32 s22, v253, 52
	v_lshl_add_u64 v[42:43], s[2:3], 0, v[2:3]
	v_lshlrev_b32_e32 v2, 3, v1
	v_readlane_b32 s23, v253, 53
	v_or_b32_e32 v4, 0x100, v0
	v_or_b32_e32 v6, 0x200, v0
	v_or_b32_e32 v8, 0x300, v0
	v_lshl_add_u64 v[2:3], s[22:23], 0, v[2:3]
	s_mov_b64 s[2:3], 0x7a00000
	v_lshl_add_u64 v[44:45], v[2:3], 0, s[2:3]
	s_mov_b64 s[2:3], 0
	v_lshlrev_b32_e32 v16, 2, v0
	v_lshlrev_b32_e32 v46, 2, v4
	v_lshlrev_b32_e32 v48, 2, v6
	v_lshlrev_b32_e32 v50, 2, v8
	v_lshlrev_b32_e32 v52, 2, v10
	v_lshlrev_b32_e32 v54, 2, v12
	v_lshlrev_b32_e32 v56, 2, v14
	v_lshlrev_b32_e32 v58, 2, v18
	v_readlane_b32 s9, v253, 39
	v_readlane_b32 s10, v253, 40
	v_readlane_b32 s11, v253, 41
	v_readlane_b32 s12, v253, 42
	v_readlane_b32 s13, v253, 43
	v_readlane_b32 s14, v253, 44
	v_readlane_b32 s15, v253, 45
	v_readlane_b32 s16, v253, 46
	v_readlane_b32 s17, v253, 47
	v_readlane_b32 s18, v253, 48
	v_readlane_b32 s19, v253, 49
	v_readlane_b32 s20, v253, 50
	v_readlane_b32 s21, v253, 51
	v_readfirstlane_b32 s2, v30
	v_readfirstlane_b32 s4, v42
	v_readfirstlane_b32 s5, v43
	v_readfirstlane_b32 s8, v32
	v_readfirstlane_b32 s9, v33
	v_readfirstlane_b32 s10, v44
	v_readfirstlane_b32 s11, v45
	v_and_b32_e32 v18, 63, v221
	v_lshlrev_b32_e32 v18, 4, v18
	v_add_u32_e32 v19, 0x1000, v18
	s_nop 2
	global_load_dwordx4 v[76:79], v18, s[8:9] offset:0
	global_load_dwordx4 v[80:83], v18, s[8:9] offset:1024
	global_load_dwordx4 v[84:87], v18, s[8:9] offset:2048
	global_load_dwordx4 v[88:91], v18, s[8:9] offset:3072
	global_load_dwordx4 v[92:95], v19, s[8:9] offset:0
	global_load_dwordx4 v[96:99], v19, s[8:9] offset:1024
	global_load_dwordx4 v[100:103], v19, s[8:9] offset:2048
	global_load_dwordx4 v[104:107], v19, s[8:9] offset:3072
	s_lshl_b32 s16, s2, 13
	v_add_u32_e32 v20, s16, v18
	v_add_u32_e32 v21, s16, v19
	global_load_dwordx4 v[108:111], v20, s[4:5] offset:0
	global_load_dwordx4 v[112:115], v20, s[4:5] offset:1024
	global_load_dwordx4 v[116:119], v20, s[4:5] offset:2048
	global_load_dwordx4 v[120:123], v20, s[4:5] offset:3072
	global_load_dwordx4 v[124:127], v21, s[4:5] offset:0
	global_load_dwordx4 v[128:131], v21, s[4:5] offset:1024
	global_load_dwordx4 v[132:135], v21, s[4:5] offset:2048
	global_load_dwordx4 v[136:139], v21, s[4:5] offset:3072
.Lnorm_n1_loop:
	s_lshr_b32 s16, s2, 11
	s_mul_i32 s16, s16, 0xc000
	s_add_u32 s12, s24, s16
	s_addc_u32 s13, s25, 0
	s_add_u32 s14, s12, 0x0
	s_addc_u32 s15, s13, 0
	s_add_u32 s12, s12, 0x2000
	s_addc_u32 s13, s13, 0
	global_load_dwordx4 v[148:151], v18, s[12:13] offset:0
	global_load_dwordx4 v[232:235], v18, s[14:15] offset:0
	global_load_dwordx4 v[152:155], v18, s[12:13] offset:1024
	global_load_dwordx4 v[236:239], v18, s[14:15] offset:1024
	global_load_dwordx4 v[156:159], v18, s[12:13] offset:2048
	global_load_dwordx4 v[240:243], v18, s[14:15] offset:2048
	global_load_dwordx4 v[160:163], v18, s[12:13] offset:3072
	global_load_dwordx4 v[244:247], v18, s[14:15] offset:3072
	global_load_dwordx4 v[164:167], v19, s[12:13] offset:0
	global_load_dwordx4 v[248:251], v19, s[14:15] offset:0
	global_load_dwordx4 v[168:171], v19, s[12:13] offset:1024
	global_load_dwordx4 v[8:11], v19, s[14:15] offset:1024
	global_load_dwordx4 v[0:3], v19, s[12:13] offset:2048
	global_load_dwordx4 v[12:15], v19, s[14:15] offset:2048
	global_load_dwordx4 v[4:7], v19, s[12:13] offset:3072
	global_load_dwordx4 v[208:211], v19, s[14:15] offset:3072
	s_add_i32 s3, s2, s60
	s_cmp_gt_i32 s3, s6
	s_cselect_b32 s17, s2, s3
	s_lshl_b32 s16, s17, 13
	v_add_u32_e32 v20, s16, v18
	v_add_u32_e32 v21, s16, v19
	global_load_dwordx4 v[176:179], v20, s[4:5] offset:0
	global_load_dwordx4 v[180:183], v20, s[4:5] offset:1024
	global_load_dwordx4 v[184:187], v20, s[4:5] offset:2048
	global_load_dwordx4 v[188:191], v20, s[4:5] offset:3072
	global_load_dwordx4 v[192:195], v21, s[4:5] offset:0
	global_load_dwordx4 v[196:199], v21, s[4:5] offset:1024
	global_load_dwordx4 v[200:203], v21, s[4:5] offset:2048
	global_load_dwordx4 v[204:207], v21, s[4:5] offset:3072
	s_waitcnt vmcnt(24)
	v_mul_f32_e32 v23, v109, v109
	v_fmac_f32_e32 v23, v108, v108
	v_fmac_f32_e32 v23, v110, v110
	v_fmac_f32_e32 v23, v111, v111
	v_mul_f32_e32 v24, v113, v113
	v_fmac_f32_e32 v24, v112, v112
	v_fmac_f32_e32 v24, v114, v114
	v_fmac_f32_e32 v24, v115, v115
	v_add_f32_e32 v23, v23, v24
	v_mul_f32_e32 v24, v117, v117
	v_fmac_f32_e32 v24, v116, v116
	v_fmac_f32_e32 v24, v118, v118
	v_fmac_f32_e32 v24, v119, v119
	v_add_f32_e32 v23, v23, v24
	v_mul_f32_e32 v24, v121, v121
	v_fmac_f32_e32 v24, v120, v120
	v_fmac_f32_e32 v24, v122, v122
	v_fmac_f32_e32 v24, v123, v123
	v_add_f32_e32 v23, v23, v24
	v_mul_f32_e32 v24, v125, v125
	v_fmac_f32_e32 v24, v124, v124
	v_fmac_f32_e32 v24, v126, v126
	v_fmac_f32_e32 v24, v127, v127
	v_add_f32_e32 v23, v23, v24
	v_mul_f32_e32 v24, v129, v129
	v_fmac_f32_e32 v24, v128, v128
	v_fmac_f32_e32 v24, v130, v130
	v_fmac_f32_e32 v24, v131, v131
	v_add_f32_e32 v23, v23, v24
	v_mul_f32_e32 v24, v133, v133
	v_fmac_f32_e32 v24, v132, v132
	v_fmac_f32_e32 v24, v134, v134
	v_fmac_f32_e32 v24, v135, v135
	v_add_f32_e32 v23, v23, v24
	v_mul_f32_e32 v24, v137, v137
	v_fmac_f32_e32 v24, v136, v136
	v_fmac_f32_e32 v24, v138, v138
	v_fmac_f32_e32 v24, v139, v139
	v_add_f32_e32 v23, v23, v24
	s_nop 0
	ds_bpermute_b32 v24, v66, v23
	s_waitcnt lgkmcnt(0)
	v_add_f32_e32 v23, v23, v24
	s_nop 0
	ds_bpermute_b32 v24, v67, v23
	s_waitcnt lgkmcnt(0)
	v_add_f32_e32 v23, v23, v24
	s_nop 0
	ds_bpermute_b32 v24, v68, v23
	s_waitcnt lgkmcnt(0)
	v_add_f32_e32 v23, v23, v24
	s_nop 0
	ds_bpermute_b32 v24, v69, v23
	s_waitcnt lgkmcnt(0)
	v_add_f32_e32 v23, v23, v24
	s_nop 0
	ds_bpermute_b32 v24, v70, v23
	s_waitcnt lgkmcnt(0)
	v_add_f32_e32 v23, v23, v24
	s_nop 0
	ds_bpermute_b32 v24, v71, v23
	s_waitcnt lgkmcnt(0)
	v_add_f32_e32 v23, v23, v24
	v_fmamk_f32 v23, v23, 0x3a000000, v216
	v_mul_f32_e32 v24, 0x4b800000, v23
	v_cmp_gt_f32_e32 vcc, s45, v23
	s_nop 1
	v_cndmask_b32_e32 v23, v23, v24, vcc
	v_rsq_f32_e32 v23, v23
	s_nop 0
	v_mul_f32_e32 v24, 0x45800000, v23
	v_cndmask_b32_e32 v25, v23, v24, vcc
	s_lshl_b32 s16, s2, 12
	v_lshrrev_b32_e32 v22, 1, v18
	v_add_u32_e32 v22, s16, v22
	s_waitcnt vmcnt(8)
	v_mul_f32_e32 v108, v108, v25
	v_mul_f32_e32 v109, v109, v25
	v_mul_f32_e32 v110, v110, v25
	v_mul_f32_e32 v111, v111, v25
	v_mul_f32_e32 v108, v76, v108
	v_mul_f32_e32 v109, v77, v109
	v_mul_f32_e32 v110, v78, v110
	v_mul_f32_e32 v111, v79, v111
	v_add_f32_e32 v148, 1.0, v148
	v_add_f32_e32 v149, 1.0, v149
	v_add_f32_e32 v150, 1.0, v150
	v_add_f32_e32 v151, 1.0, v151
	v_fma_f32 v108, v148, v108, v232
	v_fma_f32 v109, v149, v109, v233
	v_fma_f32 v110, v150, v110, v234
	v_fma_f32 v111, v151, v111, v235
	v_cvt_pk_bf16_f32 v108, v108, v109
	v_cvt_pk_bf16_f32 v109, v110, v111
	global_store_dwordx2 v22, v[108:109], s[10:11] offset:0
	v_mul_f32_e32 v112, v112, v25
	v_mul_f32_e32 v113, v113, v25
	v_mul_f32_e32 v114, v114, v25
	v_mul_f32_e32 v115, v115, v25
	v_mul_f32_e32 v112, v80, v112
	v_mul_f32_e32 v113, v81, v113
	v_mul_f32_e32 v114, v82, v114
	v_mul_f32_e32 v115, v83, v115
	v_add_f32_e32 v152, 1.0, v152
	v_add_f32_e32 v153, 1.0, v153
	v_add_f32_e32 v154, 1.0, v154
	v_add_f32_e32 v155, 1.0, v155
	v_fma_f32 v112, v152, v112, v236
	v_fma_f32 v113, v153, v113, v237
	v_fma_f32 v114, v154, v114, v238
	v_fma_f32 v115, v155, v115, v239
	v_cvt_pk_bf16_f32 v112, v112, v113
	v_cvt_pk_bf16_f32 v113, v114, v115
	global_store_dwordx2 v22, v[112:113], s[10:11] offset:512
	v_mul_f32_e32 v116, v116, v25
	v_mul_f32_e32 v117, v117, v25
	v_mul_f32_e32 v118, v118, v25
	v_mul_f32_e32 v119, v119, v25
	v_mul_f32_e32 v116, v84, v116
	v_mul_f32_e32 v117, v85, v117
	v_mul_f32_e32 v118, v86, v118
	v_mul_f32_e32 v119, v87, v119
	v_add_f32_e32 v156, 1.0, v156
	v_add_f32_e32 v157, 1.0, v157
	v_add_f32_e32 v158, 1.0, v158
	v_add_f32_e32 v159, 1.0, v159
	v_fma_f32 v116, v156, v116, v240
	v_fma_f32 v117, v157, v117, v241
	v_fma_f32 v118, v158, v118, v242
	v_fma_f32 v119, v159, v119, v243
	v_cvt_pk_bf16_f32 v116, v116, v117
	v_cvt_pk_bf16_f32 v117, v118, v119
	global_store_dwordx2 v22, v[116:117], s[10:11] offset:1024
	v_mul_f32_e32 v120, v120, v25
	v_mul_f32_e32 v121, v121, v25
	v_mul_f32_e32 v122, v122, v25
	v_mul_f32_e32 v123, v123, v25
	v_mul_f32_e32 v120, v88, v120
	v_mul_f32_e32 v121, v89, v121
	v_mul_f32_e32 v122, v90, v122
	v_mul_f32_e32 v123, v91, v123
	v_add_f32_e32 v160, 1.0, v160
	v_add_f32_e32 v161, 1.0, v161
	v_add_f32_e32 v162, 1.0, v162
	v_add_f32_e32 v163, 1.0, v163
	v_fma_f32 v120, v160, v120, v244
	v_fma_f32 v121, v161, v121, v245
	v_fma_f32 v122, v162, v122, v246
	v_fma_f32 v123, v163, v123, v247
	v_cvt_pk_bf16_f32 v120, v120, v121
	v_cvt_pk_bf16_f32 v121, v122, v123
	global_store_dwordx2 v22, v[120:121], s[10:11] offset:1536
	v_mul_f32_e32 v124, v124, v25
	v_mul_f32_e32 v125, v125, v25
	v_mul_f32_e32 v126, v126, v25
	v_mul_f32_e32 v127, v127, v25
	v_mul_f32_e32 v124, v92, v124
	v_mul_f32_e32 v125, v93, v125
	v_mul_f32_e32 v126, v94, v126
	v_mul_f32_e32 v127, v95, v127
	v_add_f32_e32 v164, 1.0, v164
	v_add_f32_e32 v165, 1.0, v165
	v_add_f32_e32 v166, 1.0, v166
	v_add_f32_e32 v167, 1.0, v167
	v_fma_f32 v124, v164, v124, v248
	v_fma_f32 v125, v165, v125, v249
	v_fma_f32 v126, v166, v126, v250
	v_fma_f32 v127, v167, v127, v251
	v_cvt_pk_bf16_f32 v124, v124, v125
	v_cvt_pk_bf16_f32 v125, v126, v127
	global_store_dwordx2 v22, v[124:125], s[10:11] offset:2048
	v_mul_f32_e32 v128, v128, v25
	v_mul_f32_e32 v129, v129, v25
	v_mul_f32_e32 v130, v130, v25
	v_mul_f32_e32 v131, v131, v25
	v_mul_f32_e32 v128, v96, v128
	v_mul_f32_e32 v129, v97, v129
	v_mul_f32_e32 v130, v98, v130
	v_mul_f32_e32 v131, v99, v131
	v_add_f32_e32 v168, 1.0, v168
	v_add_f32_e32 v169, 1.0, v169
	v_add_f32_e32 v170, 1.0, v170
	v_add_f32_e32 v171, 1.0, v171
	v_fma_f32 v128, v168, v128, v8
	v_fma_f32 v129, v169, v129, v9
	v_fma_f32 v130, v170, v130, v10
	v_fma_f32 v131, v171, v131, v11
	v_cvt_pk_bf16_f32 v128, v128, v129
	v_cvt_pk_bf16_f32 v129, v130, v131
	global_store_dwordx2 v22, v[128:129], s[10:11] offset:2560
	v_mul_f32_e32 v132, v132, v25
	v_mul_f32_e32 v133, v133, v25
	v_mul_f32_e32 v134, v134, v25
	v_mul_f32_e32 v135, v135, v25
	v_mul_f32_e32 v132, v100, v132
	v_mul_f32_e32 v133, v101, v133
	v_mul_f32_e32 v134, v102, v134
	v_mul_f32_e32 v135, v103, v135
	v_add_f32_e32 v0, 1.0, v0
	v_add_f32_e32 v1, 1.0, v1
	v_add_f32_e32 v2, 1.0, v2
	v_add_f32_e32 v3, 1.0, v3
	v_fma_f32 v132, v0, v132, v12
	v_fma_f32 v133, v1, v133, v13
	v_fma_f32 v134, v2, v134, v14
	v_fma_f32 v135, v3, v135, v15
	v_cvt_pk_bf16_f32 v132, v132, v133
	v_cvt_pk_bf16_f32 v133, v134, v135
	global_store_dwordx2 v22, v[132:133], s[10:11] offset:3072
	v_mul_f32_e32 v136, v136, v25
	v_mul_f32_e32 v137, v137, v25
	v_mul_f32_e32 v138, v138, v25
	v_mul_f32_e32 v139, v139, v25
	v_mul_f32_e32 v136, v104, v136
	v_mul_f32_e32 v137, v105, v137
	v_mul_f32_e32 v138, v106, v138
	v_mul_f32_e32 v139, v107, v139
	v_add_f32_e32 v4, 1.0, v4
	v_add_f32_e32 v5, 1.0, v5
	v_add_f32_e32 v6, 1.0, v6
	v_add_f32_e32 v7, 1.0, v7
	v_fma_f32 v136, v4, v136, v208
	v_fma_f32 v137, v5, v137, v209
	v_fma_f32 v138, v6, v138, v210
	v_fma_f32 v139, v7, v139, v211
	v_cvt_pk_bf16_f32 v136, v136, v137
	v_cvt_pk_bf16_f32 v137, v138, v139
	global_store_dwordx2 v22, v[136:137], s[10:11] offset:3584
	s_cmp_gt_i32 s3, s6
	s_mov_b32 s2, s3
	s_cbranch_scc1 .Lnorm_n1_done
	s_lshr_b32 s16, s2, 11
	s_mul_i32 s16, s16, 0xc000
	s_add_u32 s12, s24, s16
	s_addc_u32 s13, s25, 0
	s_add_u32 s14, s12, 0x0
	s_addc_u32 s15, s13, 0
	s_add_u32 s12, s12, 0x2000
	s_addc_u32 s13, s13, 0
	global_load_dwordx4 v[148:151], v18, s[12:13] offset:0
	global_load_dwordx4 v[232:235], v18, s[14:15] offset:0
	global_load_dwordx4 v[152:155], v18, s[12:13] offset:1024
	global_load_dwordx4 v[236:239], v18, s[14:15] offset:1024
	global_load_dwordx4 v[156:159], v18, s[12:13] offset:2048
	global_load_dwordx4 v[240:243], v18, s[14:15] offset:2048
	global_load_dwordx4 v[160:163], v18, s[12:13] offset:3072
	global_load_dwordx4 v[244:247], v18, s[14:15] offset:3072
	global_load_dwordx4 v[164:167], v19, s[12:13] offset:0
	global_load_dwordx4 v[248:251], v19, s[14:15] offset:0
	global_load_dwordx4 v[168:171], v19, s[12:13] offset:1024
	global_load_dwordx4 v[8:11], v19, s[14:15] offset:1024
	global_load_dwordx4 v[0:3], v19, s[12:13] offset:2048
	global_load_dwordx4 v[12:15], v19, s[14:15] offset:2048
	global_load_dwordx4 v[4:7], v19, s[12:13] offset:3072
	global_load_dwordx4 v[208:211], v19, s[14:15] offset:3072
	s_add_i32 s3, s2, s60
	s_cmp_gt_i32 s3, s6
	s_cselect_b32 s17, s2, s3
	s_lshl_b32 s16, s17, 13
	v_add_u32_e32 v20, s16, v18
	v_add_u32_e32 v21, s16, v19
	global_load_dwordx4 v[108:111], v20, s[4:5] offset:0
	global_load_dwordx4 v[112:115], v20, s[4:5] offset:1024
	global_load_dwordx4 v[116:119], v20, s[4:5] offset:2048
	global_load_dwordx4 v[120:123], v20, s[4:5] offset:3072
	global_load_dwordx4 v[124:127], v21, s[4:5] offset:0
	global_load_dwordx4 v[128:131], v21, s[4:5] offset:1024
	global_load_dwordx4 v[132:135], v21, s[4:5] offset:2048
	global_load_dwordx4 v[136:139], v21, s[4:5] offset:3072
	s_waitcnt vmcnt(24)
	v_mul_f32_e32 v23, v177, v177
	v_fmac_f32_e32 v23, v176, v176
	v_fmac_f32_e32 v23, v178, v178
	v_fmac_f32_e32 v23, v179, v179
	v_mul_f32_e32 v24, v181, v181
	v_fmac_f32_e32 v24, v180, v180
	v_fmac_f32_e32 v24, v182, v182
	v_fmac_f32_e32 v24, v183, v183
	v_add_f32_e32 v23, v23, v24
	v_mul_f32_e32 v24, v185, v185
	v_fmac_f32_e32 v24, v184, v184
	v_fmac_f32_e32 v24, v186, v186
	v_fmac_f32_e32 v24, v187, v187
	v_add_f32_e32 v23, v23, v24
	v_mul_f32_e32 v24, v189, v189
	v_fmac_f32_e32 v24, v188, v188
	v_fmac_f32_e32 v24, v190, v190
	v_fmac_f32_e32 v24, v191, v191
	v_add_f32_e32 v23, v23, v24
	v_mul_f32_e32 v24, v193, v193
	v_fmac_f32_e32 v24, v192, v192
	v_fmac_f32_e32 v24, v194, v194
	v_fmac_f32_e32 v24, v195, v195
	v_add_f32_e32 v23, v23, v24
	v_mul_f32_e32 v24, v197, v197
	v_fmac_f32_e32 v24, v196, v196
	v_fmac_f32_e32 v24, v198, v198
	v_fmac_f32_e32 v24, v199, v199
	v_add_f32_e32 v23, v23, v24
	v_mul_f32_e32 v24, v201, v201
	v_fmac_f32_e32 v24, v200, v200
	v_fmac_f32_e32 v24, v202, v202
	v_fmac_f32_e32 v24, v203, v203
	v_add_f32_e32 v23, v23, v24
	v_mul_f32_e32 v24, v205, v205
	v_fmac_f32_e32 v24, v204, v204
	v_fmac_f32_e32 v24, v206, v206
	v_fmac_f32_e32 v24, v207, v207
	v_add_f32_e32 v23, v23, v24
	s_nop 0
	ds_bpermute_b32 v24, v66, v23
	s_waitcnt lgkmcnt(0)
	v_add_f32_e32 v23, v23, v24
	s_nop 0
	ds_bpermute_b32 v24, v67, v23
	s_waitcnt lgkmcnt(0)
	v_add_f32_e32 v23, v23, v24
	s_nop 0
	ds_bpermute_b32 v24, v68, v23
	s_waitcnt lgkmcnt(0)
	v_add_f32_e32 v23, v23, v24
	s_nop 0
	ds_bpermute_b32 v24, v69, v23
	s_waitcnt lgkmcnt(0)
	v_add_f32_e32 v23, v23, v24
	s_nop 0
	ds_bpermute_b32 v24, v70, v23
	s_waitcnt lgkmcnt(0)
	v_add_f32_e32 v23, v23, v24
	s_nop 0
	ds_bpermute_b32 v24, v71, v23
	s_waitcnt lgkmcnt(0)
	v_add_f32_e32 v23, v23, v24
	v_fmamk_f32 v23, v23, 0x3a000000, v216
	v_mul_f32_e32 v24, 0x4b800000, v23
	v_cmp_gt_f32_e32 vcc, s45, v23
	s_nop 1
	v_cndmask_b32_e32 v23, v23, v24, vcc
	v_rsq_f32_e32 v23, v23
	s_nop 0
	v_mul_f32_e32 v24, 0x45800000, v23
	v_cndmask_b32_e32 v25, v23, v24, vcc
	s_lshl_b32 s16, s2, 12
	v_lshrrev_b32_e32 v22, 1, v18
	v_add_u32_e32 v22, s16, v22
	s_waitcnt vmcnt(8)
	v_mul_f32_e32 v176, v176, v25
	v_mul_f32_e32 v177, v177, v25
	v_mul_f32_e32 v178, v178, v25
	v_mul_f32_e32 v179, v179, v25
	v_mul_f32_e32 v176, v76, v176
	v_mul_f32_e32 v177, v77, v177
	v_mul_f32_e32 v178, v78, v178
	v_mul_f32_e32 v179, v79, v179
	v_add_f32_e32 v148, 1.0, v148
	v_add_f32_e32 v149, 1.0, v149
	v_add_f32_e32 v150, 1.0, v150
	v_add_f32_e32 v151, 1.0, v151
	v_fma_f32 v176, v148, v176, v232
	v_fma_f32 v177, v149, v177, v233
	v_fma_f32 v178, v150, v178, v234
	v_fma_f32 v179, v151, v179, v235
	v_cvt_pk_bf16_f32 v176, v176, v177
	v_cvt_pk_bf16_f32 v177, v178, v179
	global_store_dwordx2 v22, v[176:177], s[10:11] offset:0
	v_mul_f32_e32 v180, v180, v25
	v_mul_f32_e32 v181, v181, v25
	v_mul_f32_e32 v182, v182, v25
	v_mul_f32_e32 v183, v183, v25
	v_mul_f32_e32 v180, v80, v180
	v_mul_f32_e32 v181, v81, v181
	v_mul_f32_e32 v182, v82, v182
	v_mul_f32_e32 v183, v83, v183
	v_add_f32_e32 v152, 1.0, v152
	v_add_f32_e32 v153, 1.0, v153
	v_add_f32_e32 v154, 1.0, v154
	v_add_f32_e32 v155, 1.0, v155
	v_fma_f32 v180, v152, v180, v236
	v_fma_f32 v181, v153, v181, v237
	v_fma_f32 v182, v154, v182, v238
	v_fma_f32 v183, v155, v183, v239
	v_cvt_pk_bf16_f32 v180, v180, v181
	v_cvt_pk_bf16_f32 v181, v182, v183
	global_store_dwordx2 v22, v[180:181], s[10:11] offset:512
	v_mul_f32_e32 v184, v184, v25
	v_mul_f32_e32 v185, v185, v25
	v_mul_f32_e32 v186, v186, v25
	v_mul_f32_e32 v187, v187, v25
	v_mul_f32_e32 v184, v84, v184
	v_mul_f32_e32 v185, v85, v185
	v_mul_f32_e32 v186, v86, v186
	v_mul_f32_e32 v187, v87, v187
	v_add_f32_e32 v156, 1.0, v156
	v_add_f32_e32 v157, 1.0, v157
	v_add_f32_e32 v158, 1.0, v158
	v_add_f32_e32 v159, 1.0, v159
	v_fma_f32 v184, v156, v184, v240
	v_fma_f32 v185, v157, v185, v241
	v_fma_f32 v186, v158, v186, v242
	v_fma_f32 v187, v159, v187, v243
	v_cvt_pk_bf16_f32 v184, v184, v185
	v_cvt_pk_bf16_f32 v185, v186, v187
	global_store_dwordx2 v22, v[184:185], s[10:11] offset:1024
	v_mul_f32_e32 v188, v188, v25
	v_mul_f32_e32 v189, v189, v25
	v_mul_f32_e32 v190, v190, v25
	v_mul_f32_e32 v191, v191, v25
	v_mul_f32_e32 v188, v88, v188
	v_mul_f32_e32 v189, v89, v189
	v_mul_f32_e32 v190, v90, v190
	v_mul_f32_e32 v191, v91, v191
	v_add_f32_e32 v160, 1.0, v160
	v_add_f32_e32 v161, 1.0, v161
	v_add_f32_e32 v162, 1.0, v162
	v_add_f32_e32 v163, 1.0, v163
	v_fma_f32 v188, v160, v188, v244
	v_fma_f32 v189, v161, v189, v245
	v_fma_f32 v190, v162, v190, v246
	v_fma_f32 v191, v163, v191, v247
	v_cvt_pk_bf16_f32 v188, v188, v189
	v_cvt_pk_bf16_f32 v189, v190, v191
	global_store_dwordx2 v22, v[188:189], s[10:11] offset:1536
	v_mul_f32_e32 v192, v192, v25
	v_mul_f32_e32 v193, v193, v25
	v_mul_f32_e32 v194, v194, v25
	v_mul_f32_e32 v195, v195, v25
	v_mul_f32_e32 v192, v92, v192
	v_mul_f32_e32 v193, v93, v193
	v_mul_f32_e32 v194, v94, v194
	v_mul_f32_e32 v195, v95, v195
	v_add_f32_e32 v164, 1.0, v164
	v_add_f32_e32 v165, 1.0, v165
	v_add_f32_e32 v166, 1.0, v166
	v_add_f32_e32 v167, 1.0, v167
	v_fma_f32 v192, v164, v192, v248
	v_fma_f32 v193, v165, v193, v249
	v_fma_f32 v194, v166, v194, v250
	v_fma_f32 v195, v167, v195, v251
	v_cvt_pk_bf16_f32 v192, v192, v193
	v_cvt_pk_bf16_f32 v193, v194, v195
	global_store_dwordx2 v22, v[192:193], s[10:11] offset:2048
	v_mul_f32_e32 v196, v196, v25
	v_mul_f32_e32 v197, v197, v25
	v_mul_f32_e32 v198, v198, v25
	v_mul_f32_e32 v199, v199, v25
	v_mul_f32_e32 v196, v96, v196
	v_mul_f32_e32 v197, v97, v197
	v_mul_f32_e32 v198, v98, v198
	v_mul_f32_e32 v199, v99, v199
	v_add_f32_e32 v168, 1.0, v168
	v_add_f32_e32 v169, 1.0, v169
	v_add_f32_e32 v170, 1.0, v170
	v_add_f32_e32 v171, 1.0, v171
	v_fma_f32 v196, v168, v196, v8
	v_fma_f32 v197, v169, v197, v9
	v_fma_f32 v198, v170, v198, v10
	v_fma_f32 v199, v171, v199, v11
	v_cvt_pk_bf16_f32 v196, v196, v197
	v_cvt_pk_bf16_f32 v197, v198, v199
	global_store_dwordx2 v22, v[196:197], s[10:11] offset:2560
	v_mul_f32_e32 v200, v200, v25
	v_mul_f32_e32 v201, v201, v25
	v_mul_f32_e32 v202, v202, v25
	v_mul_f32_e32 v203, v203, v25
	v_mul_f32_e32 v200, v100, v200
	v_mul_f32_e32 v201, v101, v201
	v_mul_f32_e32 v202, v102, v202
	v_mul_f32_e32 v203, v103, v203
	v_add_f32_e32 v0, 1.0, v0
	v_add_f32_e32 v1, 1.0, v1
	v_add_f32_e32 v2, 1.0, v2
	v_add_f32_e32 v3, 1.0, v3
	v_fma_f32 v200, v0, v200, v12
	v_fma_f32 v201, v1, v201, v13
	v_fma_f32 v202, v2, v202, v14
	v_fma_f32 v203, v3, v203, v15
	v_cvt_pk_bf16_f32 v200, v200, v201
	v_cvt_pk_bf16_f32 v201, v202, v203
	global_store_dwordx2 v22, v[200:201], s[10:11] offset:3072
	v_mul_f32_e32 v204, v204, v25
	v_mul_f32_e32 v205, v205, v25
	v_mul_f32_e32 v206, v206, v25
	v_mul_f32_e32 v207, v207, v25
	v_mul_f32_e32 v204, v104, v204
	v_mul_f32_e32 v205, v105, v205
	v_mul_f32_e32 v206, v106, v206
	v_mul_f32_e32 v207, v107, v207
	v_add_f32_e32 v4, 1.0, v4
	v_add_f32_e32 v5, 1.0, v5
	v_add_f32_e32 v6, 1.0, v6
	v_add_f32_e32 v7, 1.0, v7
	v_fma_f32 v204, v4, v204, v208
	v_fma_f32 v205, v5, v205, v209
	v_fma_f32 v206, v6, v206, v210
	v_fma_f32 v207, v7, v207, v211
	v_cvt_pk_bf16_f32 v204, v204, v205
	v_cvt_pk_bf16_f32 v205, v206, v207
	global_store_dwordx2 v22, v[204:205], s[10:11] offset:3584
	s_cmp_gt_i32 s3, s6
	s_mov_b32 s2, s3
	s_cbranch_scc1 .Lnorm_n1_done
	s_branch .Lnorm_n1_loop
.Lnorm_n1_done:
	s_waitcnt vmcnt(0)
.LBB0_1722:
	s_or_b64 exec, exec, s[0:1]
